# NSA top-k selection: v_readlane + 64-bit key compare instead of 64 ds_bpermute steps
# speedup vs baseline: 1.0580x; 1.0208x over previous
.LBB0_95:
	v_or_b32_e32 v2, s14, v162
	v_bitop3_b32 v3, v2, 63, v180 bitop3:0x48
	v_lshl_add_u32 v3, v3, 2, v0
	ds_read_b32 v3, v3 offset:16384
	v_mov_b32_e32 v4, 0x7149f2ca
	v_cmp_gt_u32_e32 vcc, v163, v214
	v_mov_b32_e32 v5, 0
	v_sub_u32_e32 v6, 63, v163
	s_waitcnt lgkmcnt(0)
	v_cndmask_b32_e64 v3, v3, v4, s[6:7]
	v_cndmask_b32_e32 v3, v3, v205, vcc
	s_nop 0
	v_mov_b32_e32 v7, v3
	v_readlane_b32 s11, v3, 0
	s_mov_b32 s10, 63
	v_readlane_b32 s13, v3, 1
	s_mov_b32 s12, 62
	v_cmp_gt_i64_e64 s[8:9], s[10:11], v[6:7]
	v_readlane_b32 s11, v3, 2
	s_mov_b32 s10, 61
	v_addc_co_u32_e64 v5, s[8:9], 0, v5, s[8:9]
	v_cmp_gt_i64_e32 vcc, s[12:13], v[6:7]
	v_readlane_b32 s13, v3, 3
	s_mov_b32 s12, 60
	v_addc_co_u32_e32 v5, vcc, 0, v5, vcc
	v_cmp_gt_i64_e64 s[8:9], s[10:11], v[6:7]
	v_readlane_b32 s11, v3, 4
	s_mov_b32 s10, 59
	v_addc_co_u32_e64 v5, s[8:9], 0, v5, s[8:9]
	v_cmp_gt_i64_e32 vcc, s[12:13], v[6:7]
	v_readlane_b32 s13, v3, 5
	s_mov_b32 s12, 58
	v_addc_co_u32_e32 v5, vcc, 0, v5, vcc
	v_cmp_gt_i64_e64 s[8:9], s[10:11], v[6:7]
	v_readlane_b32 s11, v3, 6
	s_mov_b32 s10, 57
	v_addc_co_u32_e64 v5, s[8:9], 0, v5, s[8:9]
	v_cmp_gt_i64_e32 vcc, s[12:13], v[6:7]
	v_readlane_b32 s13, v3, 7
	s_mov_b32 s12, 56
	v_addc_co_u32_e32 v5, vcc, 0, v5, vcc
	v_cmp_gt_i64_e64 s[8:9], s[10:11], v[6:7]
	v_readlane_b32 s11, v3, 8
	s_mov_b32 s10, 55
	v_addc_co_u32_e64 v5, s[8:9], 0, v5, s[8:9]
	v_cmp_gt_i64_e32 vcc, s[12:13], v[6:7]
	v_readlane_b32 s13, v3, 9
	s_mov_b32 s12, 54
	v_addc_co_u32_e32 v5, vcc, 0, v5, vcc
	v_cmp_gt_i64_e64 s[8:9], s[10:11], v[6:7]
	v_readlane_b32 s11, v3, 10
	s_mov_b32 s10, 53
	v_addc_co_u32_e64 v5, s[8:9], 0, v5, s[8:9]
	v_cmp_gt_i64_e32 vcc, s[12:13], v[6:7]
	v_readlane_b32 s13, v3, 11
	s_mov_b32 s12, 52
	v_addc_co_u32_e32 v5, vcc, 0, v5, vcc
	v_cmp_gt_i64_e64 s[8:9], s[10:11], v[6:7]
	v_readlane_b32 s11, v3, 12
	s_mov_b32 s10, 51
	v_addc_co_u32_e64 v5, s[8:9], 0, v5, s[8:9]
	v_cmp_gt_i64_e32 vcc, s[12:13], v[6:7]
	v_readlane_b32 s13, v3, 13
	s_mov_b32 s12, 50
	v_addc_co_u32_e32 v5, vcc, 0, v5, vcc
	v_cmp_gt_i64_e64 s[8:9], s[10:11], v[6:7]
	v_readlane_b32 s11, v3, 14
	s_mov_b32 s10, 49
	v_addc_co_u32_e64 v5, s[8:9], 0, v5, s[8:9]
	v_cmp_gt_i64_e32 vcc, s[12:13], v[6:7]
	v_readlane_b32 s13, v3, 15
	s_mov_b32 s12, 48
	v_addc_co_u32_e32 v5, vcc, 0, v5, vcc
	v_cmp_gt_i64_e64 s[8:9], s[10:11], v[6:7]
	v_readlane_b32 s11, v3, 16
	s_mov_b32 s10, 47
	v_addc_co_u32_e64 v5, s[8:9], 0, v5, s[8:9]
	v_cmp_gt_i64_e32 vcc, s[12:13], v[6:7]
	v_readlane_b32 s13, v3, 17
	s_mov_b32 s12, 46
	v_addc_co_u32_e32 v5, vcc, 0, v5, vcc
	v_cmp_gt_i64_e64 s[8:9], s[10:11], v[6:7]
	v_readlane_b32 s11, v3, 18
	s_mov_b32 s10, 45
	v_addc_co_u32_e64 v5, s[8:9], 0, v5, s[8:9]
	v_cmp_gt_i64_e32 vcc, s[12:13], v[6:7]
	v_readlane_b32 s13, v3, 19
	s_mov_b32 s12, 44
	v_addc_co_u32_e32 v5, vcc, 0, v5, vcc
	v_cmp_gt_i64_e64 s[8:9], s[10:11], v[6:7]
	v_readlane_b32 s11, v3, 20
	s_mov_b32 s10, 43
	v_addc_co_u32_e64 v5, s[8:9], 0, v5, s[8:9]
	v_cmp_gt_i64_e32 vcc, s[12:13], v[6:7]
	v_readlane_b32 s13, v3, 21
	s_mov_b32 s12, 42
	v_addc_co_u32_e32 v5, vcc, 0, v5, vcc
	v_cmp_gt_i64_e64 s[8:9], s[10:11], v[6:7]
	v_readlane_b32 s11, v3, 22
	s_mov_b32 s10, 41
	v_addc_co_u32_e64 v5, s[8:9], 0, v5, s[8:9]
	v_cmp_gt_i64_e32 vcc, s[12:13], v[6:7]
	v_readlane_b32 s13, v3, 23
	s_mov_b32 s12, 40
	v_addc_co_u32_e32 v5, vcc, 0, v5, vcc
	v_cmp_gt_i64_e64 s[8:9], s[10:11], v[6:7]
	v_readlane_b32 s11, v3, 24
	s_mov_b32 s10, 39
	v_addc_co_u32_e64 v5, s[8:9], 0, v5, s[8:9]
	v_cmp_gt_i64_e32 vcc, s[12:13], v[6:7]
	v_readlane_b32 s13, v3, 25
	s_mov_b32 s12, 38
	v_addc_co_u32_e32 v5, vcc, 0, v5, vcc
	v_cmp_gt_i64_e64 s[8:9], s[10:11], v[6:7]
	v_readlane_b32 s11, v3, 26
	s_mov_b32 s10, 37
	v_addc_co_u32_e64 v5, s[8:9], 0, v5, s[8:9]
	v_cmp_gt_i64_e32 vcc, s[12:13], v[6:7]
	v_readlane_b32 s13, v3, 27
	s_mov_b32 s12, 36
	v_addc_co_u32_e32 v5, vcc, 0, v5, vcc
	v_cmp_gt_i64_e64 s[8:9], s[10:11], v[6:7]
	v_readlane_b32 s11, v3, 28
	s_mov_b32 s10, 35
	v_addc_co_u32_e64 v5, s[8:9], 0, v5, s[8:9]
	v_cmp_gt_i64_e32 vcc, s[12:13], v[6:7]
	v_readlane_b32 s13, v3, 29
	s_mov_b32 s12, 34
	v_addc_co_u32_e32 v5, vcc, 0, v5, vcc
	v_cmp_gt_i64_e64 s[8:9], s[10:11], v[6:7]
	v_readlane_b32 s11, v3, 30
	s_mov_b32 s10, 33
	v_addc_co_u32_e64 v5, s[8:9], 0, v5, s[8:9]
	v_cmp_gt_i64_e32 vcc, s[12:13], v[6:7]
	v_readlane_b32 s13, v3, 31
	s_mov_b32 s12, 32
	v_addc_co_u32_e32 v5, vcc, 0, v5, vcc
	v_cmp_gt_i64_e64 s[8:9], s[10:11], v[6:7]
	v_readlane_b32 s11, v3, 32
	s_mov_b32 s10, 31
	v_addc_co_u32_e64 v5, s[8:9], 0, v5, s[8:9]
	v_cmp_gt_i64_e32 vcc, s[12:13], v[6:7]
	v_readlane_b32 s13, v3, 33
	s_mov_b32 s12, 30
	v_addc_co_u32_e32 v5, vcc, 0, v5, vcc
	v_cmp_gt_i64_e64 s[8:9], s[10:11], v[6:7]
	v_readlane_b32 s11, v3, 34
	s_mov_b32 s10, 29
	v_addc_co_u32_e64 v5, s[8:9], 0, v5, s[8:9]
	v_cmp_gt_i64_e32 vcc, s[12:13], v[6:7]
	v_readlane_b32 s13, v3, 35
	s_mov_b32 s12, 28
	v_addc_co_u32_e32 v5, vcc, 0, v5, vcc
	v_cmp_gt_i64_e64 s[8:9], s[10:11], v[6:7]
	v_readlane_b32 s11, v3, 36
	s_mov_b32 s10, 27
	v_addc_co_u32_e64 v5, s[8:9], 0, v5, s[8:9]
	v_cmp_gt_i64_e32 vcc, s[12:13], v[6:7]
	v_readlane_b32 s13, v3, 37
	s_mov_b32 s12, 26
	v_addc_co_u32_e32 v5, vcc, 0, v5, vcc
	v_cmp_gt_i64_e64 s[8:9], s[10:11], v[6:7]
	v_readlane_b32 s11, v3, 38
	s_mov_b32 s10, 25
	v_addc_co_u32_e64 v5, s[8:9], 0, v5, s[8:9]
	v_cmp_gt_i64_e32 vcc, s[12:13], v[6:7]
	v_readlane_b32 s13, v3, 39
	s_mov_b32 s12, 24
	v_addc_co_u32_e32 v5, vcc, 0, v5, vcc
	v_cmp_gt_i64_e64 s[8:9], s[10:11], v[6:7]
	v_readlane_b32 s11, v3, 40
	s_mov_b32 s10, 23
	v_addc_co_u32_e64 v5, s[8:9], 0, v5, s[8:9]
	v_cmp_gt_i64_e32 vcc, s[12:13], v[6:7]
	v_readlane_b32 s13, v3, 41
	s_mov_b32 s12, 22
	v_addc_co_u32_e32 v5, vcc, 0, v5, vcc
	v_cmp_gt_i64_e64 s[8:9], s[10:11], v[6:7]
	v_readlane_b32 s11, v3, 42
	s_mov_b32 s10, 21
	v_addc_co_u32_e64 v5, s[8:9], 0, v5, s[8:9]
	v_cmp_gt_i64_e32 vcc, s[12:13], v[6:7]
	v_readlane_b32 s13, v3, 43
	s_mov_b32 s12, 20
	v_addc_co_u32_e32 v5, vcc, 0, v5, vcc
	v_cmp_gt_i64_e64 s[8:9], s[10:11], v[6:7]
	v_readlane_b32 s11, v3, 44
	s_mov_b32 s10, 19
	v_addc_co_u32_e64 v5, s[8:9], 0, v5, s[8:9]
	v_cmp_gt_i64_e32 vcc, s[12:13], v[6:7]
	v_readlane_b32 s13, v3, 45
	s_mov_b32 s12, 18
	v_addc_co_u32_e32 v5, vcc, 0, v5, vcc
	v_cmp_gt_i64_e64 s[8:9], s[10:11], v[6:7]
	v_readlane_b32 s11, v3, 46
	s_mov_b32 s10, 17
	v_addc_co_u32_e64 v5, s[8:9], 0, v5, s[8:9]
	v_cmp_gt_i64_e32 vcc, s[12:13], v[6:7]
	v_readlane_b32 s13, v3, 47
	s_mov_b32 s12, 16
	v_addc_co_u32_e32 v5, vcc, 0, v5, vcc
	v_cmp_gt_i64_e64 s[8:9], s[10:11], v[6:7]
	v_readlane_b32 s11, v3, 48
	s_mov_b32 s10, 15
	v_addc_co_u32_e64 v5, s[8:9], 0, v5, s[8:9]
	v_cmp_gt_i64_e32 vcc, s[12:13], v[6:7]
	v_readlane_b32 s13, v3, 49
	s_mov_b32 s12, 14
	v_addc_co_u32_e32 v5, vcc, 0, v5, vcc
	v_cmp_gt_i64_e64 s[8:9], s[10:11], v[6:7]
	v_readlane_b32 s11, v3, 50
	s_mov_b32 s10, 13
	v_addc_co_u32_e64 v5, s[8:9], 0, v5, s[8:9]
	v_cmp_gt_i64_e32 vcc, s[12:13], v[6:7]
	v_readlane_b32 s13, v3, 51
	s_mov_b32 s12, 12
	v_addc_co_u32_e32 v5, vcc, 0, v5, vcc
	v_cmp_gt_i64_e64 s[8:9], s[10:11], v[6:7]
	v_readlane_b32 s11, v3, 52
	s_mov_b32 s10, 11
	v_addc_co_u32_e64 v5, s[8:9], 0, v5, s[8:9]
	v_cmp_gt_i64_e32 vcc, s[12:13], v[6:7]
	v_readlane_b32 s13, v3, 53
	s_mov_b32 s12, 10
	v_addc_co_u32_e32 v5, vcc, 0, v5, vcc
	v_cmp_gt_i64_e64 s[8:9], s[10:11], v[6:7]
	v_readlane_b32 s11, v3, 54
	s_mov_b32 s10, 9
	v_addc_co_u32_e64 v5, s[8:9], 0, v5, s[8:9]
	v_cmp_gt_i64_e32 vcc, s[12:13], v[6:7]
	v_readlane_b32 s13, v3, 55
	s_mov_b32 s12, 8
	v_addc_co_u32_e32 v5, vcc, 0, v5, vcc
	v_cmp_gt_i64_e64 s[8:9], s[10:11], v[6:7]
	v_readlane_b32 s11, v3, 56
	s_mov_b32 s10, 7
	v_addc_co_u32_e64 v5, s[8:9], 0, v5, s[8:9]
	v_cmp_gt_i64_e32 vcc, s[12:13], v[6:7]
	v_readlane_b32 s13, v3, 57
	s_mov_b32 s12, 6
	v_addc_co_u32_e32 v5, vcc, 0, v5, vcc
	v_cmp_gt_i64_e64 s[8:9], s[10:11], v[6:7]
	v_readlane_b32 s11, v3, 58
	s_mov_b32 s10, 5
	v_addc_co_u32_e64 v5, s[8:9], 0, v5, s[8:9]
	v_cmp_gt_i64_e32 vcc, s[12:13], v[6:7]
	v_readlane_b32 s13, v3, 59
	s_mov_b32 s12, 4
	v_addc_co_u32_e32 v5, vcc, 0, v5, vcc
	v_cmp_gt_i64_e64 s[8:9], s[10:11], v[6:7]
	v_readlane_b32 s11, v3, 60
	s_mov_b32 s10, 3
	v_addc_co_u32_e64 v5, s[8:9], 0, v5, s[8:9]
	v_cmp_gt_i64_e32 vcc, s[12:13], v[6:7]
	v_readlane_b32 s13, v3, 61
	s_mov_b32 s12, 2
	v_addc_co_u32_e32 v5, vcc, 0, v5, vcc
	v_cmp_gt_i64_e64 s[8:9], s[10:11], v[6:7]
	v_readlane_b32 s11, v3, 62
	s_mov_b32 s10, 1
	v_addc_co_u32_e64 v5, s[8:9], 0, v5, s[8:9]
	v_cmp_gt_i64_e32 vcc, s[12:13], v[6:7]
	v_readlane_b32 s13, v3, 63
	s_mov_b32 s12, 0
	v_addc_co_u32_e32 v5, vcc, 0, v5, vcc
	v_cmp_gt_i64_e64 s[8:9], s[10:11], v[6:7]
	s_nop 1
	v_addc_co_u32_e64 v5, s[8:9], 0, v5, s[8:9]
	v_cmp_gt_i64_e32 vcc, s[12:13], v[6:7]
	s_nop 1
	v_addc_co_u32_e32 v5, vcc, 0, v5, vcc
	s_mov_b32 s10, 0xf0c9f2ca
	v_cmp_gt_u32_e64 s[8:9], 16, v5
	v_cmp_lt_f32_e64 s[10:11], s10, v3
	s_and_b64 s[8:9], s[8:9], s[10:11]
	v_cndmask_b32_e64 v3, 0, 1, s[8:9]
	v_cmp_ne_u32_e64 s[10:11], 0, v3
	s_and_saveexec_b64 s[8:9], s[4:5]
	s_cbranch_execz .LBB0_94
	v_lshl_add_u32 v2, v2, 3, v202
	v_mov_b64_e32 v[4:5], s[10:11]
	ds_write_b64 v2, v[4:5]
	s_branch .LBB0_94
